# int8 in-projection epilogue: all 8 row-scale loads and the RoPE table loads prefetched two rows ahead into free VGPRs; the per-row vmcnt(0) drains replaced by counted waits
# speedup vs baseline: 1.0016x; 1.0006x over previous
;     __device__ __forceinline__ void operator()(Acc& acc, const Unit& u, int wr, int wc, int fr, int fq, LAS unsigned char* lds, int tid) const {
;         const unsigned row0 = u.pm * 256, pn = u.pn, colt = pn * 256 + wc * 32 + 8 * fq;
;         const bool rope = pn < 8;
;         const float sc = pn < 4 ? QSCALE : 1.0f;
;         f32x4 swv[2][2];
; #pragma unroll
;         for (int bj = 0; bj < 2; ++bj)
; #pragma unroll
;             for (int n = 0; n < 2; ++n) swv[bj][n] = ldf4(sw, colt + 128u * bj + 4u * n) * sc;
; #pragma unroll
;         for (int ai = 0; ai < 2; ++ai)
; #pragma unroll
;             for (int m = 0; m < 4; ++m) {
;                 const unsigned row = row0 + ai * 128 + wr * 64 + m * 16 + fr;
;                 const float rs = *(const float*)((const char*)sx + (row << 2));
;                 f32x4 x[2][2];
; #pragma unroll
;                 for (int bj = 0; bj < 2; ++bj)
; #pragma unroll
;                     for (int n = 0; n < 2; ++n) { const pg8::i32x4 iv = __builtin_bit_cast(pg8::i32x4, acc[ai][bj][m][n]); x[bj][n] = __builtin_convertvector(iv, f32x4) * (swv[bj][n] * rs); }
;                 if (rope) {
;                     const unsigned t = row & (SEQ - 1), d0 = 32 * (wc & 1) + 8 * fq;
;                     f32x4 v[2][2];
; #pragma unroll
;                     for (int n = 0; n < 2; ++n) { const f32x4 c = ldf4(ropec, t * 64 + d0 + 4u * n), s = ldf4(ropes, t * 64 + d0 + 4u * n);
;                         v[0][n] = x[0][n] * c - x[1][n] * s; v[1][n] = x[1][n] * c + x[0][n] * s; }
;                     h16* o = Hq + (size_t)row * 3072 + (256 * pn + 128 * (wc >> 1) + d0);
;                     store_h8(o, v[0][0], v[0][1]); store_h8(o + 64, v[1][0], v[1][1]);
.LBB0_619:
	v_mbcnt_lo_u32_b32 v146, -1, 0
	v_mbcnt_hi_u32_b32 v146, -1, v146
	s_lshl_b32 s0, s38, 8
	v_lshrrev_b32_e32 v128, 1, v146
	s_or_b32 s1, s0, s89
	v_and_b32_e32 v147, 24, v128
	v_or_b32_e32 v208, s1, v147
	s_cmp_lt_u32 s38, 4
	s_cselect_b64 vcc, -1, 0
	v_mov_b32_e32 v128, 0x3e0293ee
	v_lshlrev_b32_e32 v138, 2, v208
	v_cndmask_b32_e32 v142, 1.0, v128, vcc
	global_load_dwordx4 v[128:131], v138, s[22:23] offset:16
	global_load_dwordx4 v[134:137], v138, s[22:23]
	global_load_dwordx4 v[154:157], v138, s[22:23] offset:528
	s_nop 0
	global_load_dwordx4 v[138:141], v138, s[22:23] offset:512
	s_lshl_b32 s1, s60, 8
	s_cmp_lt_u32 s38, 8
	s_cselect_b64 s[44:45], -1, 0
	s_add_i32 s1, s1, s88
	v_cvt_f32_i32_e32 v127, v127
	v_cvt_f32_i32_e32 v126, v126
	v_cvt_f32_i32_e32 v123, v123
	v_cvt_f32_i32_e32 v122, v122
	v_cvt_f32_i32_e32 v125, v125
	v_cvt_f32_i32_e32 v124, v124
	v_cvt_f32_i32_e32 v121, v121
	v_cvt_f32_i32_e32 v120, v120
	s_or_b32 s0, s0, s74
	s_cmp_gt_u32 s38, 7
	s_mov_b64 s[60:61], 0x100
	s_waitcnt vmcnt(3)
	v_pk_mul_f32 v[130:131], v[142:143], v[130:131] op_sel_hi:[0,1]
	s_waitcnt vmcnt(2)
	v_pk_mul_f32 v[132:133], v[142:143], v[136:137] op_sel_hi:[0,1]
	v_pk_mul_f32 v[136:137], v[142:143], v[134:135] op_sel_hi:[0,1]
	v_pk_mul_f32 v[134:135], v[142:143], v[128:129] op_sel_hi:[0,1]
	s_waitcnt vmcnt(0)
	v_pk_mul_f32 v[140:141], v[142:143], v[140:141] op_sel_hi:[0,1]
	v_pk_mul_f32 v[144:145], v[142:143], v[138:139] op_sel_hi:[0,1]
	v_pk_mul_f32 v[138:139], v[142:143], v[156:157] op_sel_hi:[0,1]
	v_pk_mul_f32 v[142:143], v[142:143], v[154:155] op_sel_hi:[0,1]
	v_and_or_b32 v155, v146, 15, s1
	v_lshlrev_b32_e32 v146, 2, v155
	v_lshlrev_b32_e32 v176, 2, v155
	v_add_u32_e32 v177, 0x40, v176
	v_add_u32_e32 v178, 0x80, v176
	v_add_u32_e32 v179, 0xc0, v176
	v_add_u32_e32 v180, 0x200, v176
	v_add_u32_e32 v181, 0x240, v176
	v_add_u32_e32 v182, 0x280, v176
	v_add_u32_e32 v183, 0x2c0, v176
	s_cbranch_scc1 .Linq_norope_pf
	v_or_b32_e32 v244, s97, v147
	v_lshlrev_b32_e32 v245, 6, v155
	v_mov_b32_e32 v243, 0x1ffc0
	v_and_or_b32 v245, v245, v243, v244
	v_lshlrev_b32_e32 v245, 2, v245
	v_add_u32_e32 v242, 0x1000, v245
	global_load_dwordx4 v[184:187], v245, s[46:47] offset:16
	global_load_dwordx4 v[188:191], v245, s[46:47]
	global_load_dwordx4 v[192:195], v245, s[26:27] offset:16
	global_load_dwordx4 v[196:199], v245, s[26:27]
	global_load_dwordx4 v[212:215], v242, s[46:47] offset:16
	global_load_dwordx4 v[216:219], v242, s[46:47]
	global_load_dwordx4 v[220:223], v242, s[26:27] offset:16
	global_load_dwordx4 v[224:227], v242, s[26:27]
.Linq_norope_pf:
	global_load_dword v176, v176, s[16:17]
	global_load_dword v177, v177, s[16:17]
	global_load_dword v178, v178, s[16:17]
	global_load_dword v179, v179, s[16:17]
	global_load_dword v180, v180, s[16:17]
	global_load_dword v181, v181, s[16:17]
	global_load_dword v182, v182, s[16:17]
	global_load_dword v183, v183, s[16:17]
	v_or_b32_e32 v154, s97, v147
	v_or_b32_e32 v128, s0, v154
	v_mov_b32_e32 v129, v209
	s_waitcnt vmcnt(0)
	v_mov_b32_e32 v146, v176
	v_pk_mul_f32 v[156:157], v[132:133], v[146:147] op_sel_hi:[1,0]
	s_nop 0
	v_pk_mul_f32 v[126:127], v[156:157], v[126:127]
	v_pk_mul_f32 v[156:157], v[130:131], v[146:147] op_sel_hi:[1,0]
	v_pk_mul_f32 v[158:159], v[136:137], v[146:147] op_sel_hi:[1,0]
	v_pk_mul_f32 v[122:123], v[156:157], v[122:123]
	v_cvt_f32_i32_e32 v157, v117
	v_cvt_f32_i32_e32 v156, v116
	v_cvt_f32_i32_e32 v117, v119
	v_cvt_f32_i32_e32 v116, v118
	v_pk_mul_f32 v[124:125], v[158:159], v[124:125]
	v_pk_mul_f32 v[158:159], v[134:135], v[146:147] op_sel_hi:[1,0]
	v_pk_mul_f32 v[118:119], v[140:141], v[146:147] op_sel_hi:[1,0]
	v_pk_mul_f32 v[120:121], v[158:159], v[120:121]
	v_pk_mul_f32 v[158:159], v[144:145], v[146:147] op_sel_hi:[1,0]
	v_pk_mul_f32 v[116:117], v[118:119], v[116:117]
	v_pk_mul_f32 v[118:119], v[158:159], v[156:157]
	v_cvt_f32_i32_e32 v157, v113
	v_cvt_f32_i32_e32 v156, v112
	v_cvt_f32_i32_e32 v113, v115
	v_cvt_f32_i32_e32 v112, v114
	v_pk_mul_f32 v[114:115], v[138:139], v[146:147] op_sel_hi:[1,0]
	v_pk_mul_f32 v[146:147], v[142:143], v[146:147] op_sel_hi:[1,0]
	v_pk_mul_f32 v[112:113], v[114:115], v[112:113]
	v_pk_mul_f32 v[114:115], v[146:147], v[156:157]
	s_cbranch_scc1 .LBB0_621
	v_lshlrev_b32_e32 v146, 6, v155
	s_mov_b32 s0, 0x1f3c0
	v_and_or_b32 v146, v146, s0, v154
	v_lshlrev_b32_e32 v146, 2, v146
	v_mov_b64_e32 v[156:157], v[184:185]
	v_mov_b64_e32 v[158:159], v[186:187]
	v_mov_b64_e32 v[160:161], v[188:189]
	v_mov_b64_e32 v[162:163], v[190:191]
	v_mov_b64_e32 v[164:165], v[192:193]
	v_mov_b64_e32 v[166:167], v[194:195]
	v_mov_b64_e32 v[168:169], v[196:197]
	v_mov_b64_e32 v[170:171], v[198:199]
	v_add_u32_e32 v242, 0x2000, v245
	global_load_dwordx4 v[184:187], v242, s[46:47] offset:16
	global_load_dwordx4 v[188:191], v242, s[46:47]
	global_load_dwordx4 v[192:195], v242, s[26:27] offset:16
	global_load_dwordx4 v[196:199], v242, s[26:27]
	s_mov_b64 s[38:39], 0x80
	v_pk_mul_f32 v[146:147], v[116:117], v[170:171]
	v_pk_mul_f32 v[172:173], v[118:119], v[168:169]
	v_pk_fma_f32 v[174:175], v[126:127], v[162:163], v[146:147] neg_lo:[0,0,1] neg_hi:[0,0,1]
	v_pk_fma_f32 v[172:173], v[124:125], v[160:161], v[172:173] neg_lo:[0,0,1] neg_hi:[0,0,1]
	v_pk_mul_f32 v[126:127], v[126:127], v[170:171]
	v_pk_mul_f32 v[124:125], v[124:125], v[168:169]
	v_pk_fma_f32 v[116:117], v[116:117], v[162:163], v[126:127]
	v_pk_fma_f32 v[118:119], v[118:119], v[160:161], v[124:125]
	v_pk_mul_f32 v[124:125], v[112:113], v[166:167]
	v_pk_mul_f32 v[126:127], v[114:115], v[164:165]
	v_pk_fma_f32 v[162:163], v[122:123], v[158:159], v[124:125] neg_lo:[0,0,1] neg_hi:[0,0,1]
	v_pk_fma_f32 v[160:161], v[120:121], v[156:157], v[126:127] neg_lo:[0,0,1] neg_hi:[0,0,1]
	v_pk_mul_f32 v[122:123], v[122:123], v[166:167]
	v_pk_mul_f32 v[120:121], v[120:121], v[164:165]
	v_pk_fma_f32 v[112:113], v[112:113], v[158:159], v[122:123]
	v_pk_fma_f32 v[114:115], v[114:115], v[156:157], v[120:121]
	v_mov_b64_e32 v[124:125], v[172:173]
	v_mov_b64_e32 v[120:121], v[160:161]
	v_mov_b64_e32 v[146:147], v[128:129]
	v_mov_b64_e32 v[126:127], v[174:175]
	v_mov_b64_e32 v[122:123], v[162:163]
	s_branch .LBB0_622

;     __device__ __forceinline__ void operator()(Acc& acc, const Unit& u, int wr, int wc, int fr, int fq, LAS unsigned char* lds, int tid) const {
;     ...
;             for (int m = 0; m < 4; ++m) {
;                 const unsigned row = row0 + ai * 128 + wr * 64 + m * 16 + fr;
;                 const float rs = *(const float*)((const char*)sx + (row << 2));
;                 f32x4 x[2][2];
; #pragma unroll
;                 for (int bj = 0; bj < 2; ++bj)
; #pragma unroll
;                     for (int n = 0; n < 2; ++n) { const pg8::i32x4 iv = __builtin_bit_cast(pg8::i32x4, acc[ai][bj][m][n]); x[bj][n] = __builtin_convertvector(iv, f32x4) * (swv[bj][n] * rs); }
;                 if (rope) {
;                     const unsigned t = row & (SEQ - 1), d0 = 32 * (wc & 1) + 8 * fq;
;                     f32x4 v[2][2];
; #pragma unroll
;                     for (int n = 0; n < 2; ++n) { const f32x4 c = ldf4(ropec, t * 64 + d0 + 4u * n), s = ldf4(ropes, t * 64 + d0 + 4u * n);
;                         v[0][n] = x[0][n] * c - x[1][n] * s; v[1][n] = x[1][n] * c + x[0][n] * s; }
;                     h16* o = Hq + (size_t)row * 3072 + (256 * pn + 128 * (wc >> 1) + d0);
;                     store_h8(o, v[0][0], v[0][1]); store_h8(o + 64, v[1][0], v[1][1]);
;                 } else {
;                     h16* o = Hq + (size_t)row * 3072 + colt;
;                     store_h8(o, x[0][0], x[0][1]); store_h8(o + 128, x[1][0], x[1][1]);
.LBB0_622:
	v_mov_b64_e32 v[156:157], s[76:77]
	v_mad_u64_u32 v[156:157], s[0:1], v155, s35, v[156:157]
	v_lshl_add_u64 v[146:147], v[146:147], 1, v[156:157]
	v_cvt_pk_f16_f32 v124, v124, v125
	v_cvt_pk_f16_f32 v125, v126, v127
	v_cvt_pk_f16_f32 v126, v120, v121
	v_cvt_pk_f16_f32 v127, v122, v123
	v_lshl_add_u64 v[122:123], v[146:147], 0, s[38:39]
	v_cvt_pk_f16_f32 v118, v118, v119
	v_cvt_pk_f16_f32 v119, v116, v117
	v_cvt_pk_f16_f32 v120, v114, v115
	v_cvt_pk_f16_f32 v121, v112, v113
	global_store_dwordx4 v[146:147], v[124:127], off
	global_store_dwordx4 v[122:123], v[118:121], off
	v_or_b32_e32 v114, 16, v155
	v_lshlrev_b32_e32 v112, 2, v114
	v_cvt_f32_i32_e32 v109, v109
	v_cvt_f32_i32_e32 v108, v108
	v_cvt_f32_i32_e32 v111, v111
	v_cvt_f32_i32_e32 v110, v110
	v_cvt_f32_i32_e32 v105, v105
	v_cvt_f32_i32_e32 v104, v104
	v_cvt_f32_i32_e32 v107, v107
	v_cvt_f32_i32_e32 v106, v106
	v_cvt_f32_i32_e32 v117, v101
	v_cvt_f32_i32_e32 v116, v100
	v_cvt_f32_i32_e32 v119, v103
	v_cvt_f32_i32_e32 v118, v102
	v_cvt_f32_i32_e32 v121, v97
	v_cvt_f32_i32_e32 v120, v96
	v_cvt_f32_i32_e32 v123, v99
	v_cvt_f32_i32_e32 v122, v98
	v_cndmask_b32_e64 v96, 0, 1, s[44:45]
	v_cmp_ne_u32_e64 s[38:39], 1, v96
	s_andn2_b64 vcc, exec, s[44:45]
	v_mov_b32_e32 v112, v177
	v_pk_mul_f32 v[96:97], v[132:133], v[112:113] op_sel_hi:[1,0]
	v_pk_mul_f32 v[98:99], v[136:137], v[112:113] op_sel_hi:[1,0]
	v_pk_mul_f32 v[124:125], v[130:131], v[112:113] op_sel_hi:[1,0]
	v_pk_mul_f32 v[126:127], v[134:135], v[112:113] op_sel_hi:[1,0]
	v_pk_mul_f32 v[146:147], v[140:141], v[112:113] op_sel_hi:[1,0]
	v_pk_mul_f32 v[156:157], v[144:145], v[112:113] op_sel_hi:[1,0]
	v_pk_mul_f32 v[158:159], v[138:139], v[112:113] op_sel_hi:[1,0]
	v_pk_mul_f32 v[112:113], v[142:143], v[112:113] op_sel_hi:[1,0]
	v_pk_mul_f32 v[102:103], v[96:97], v[110:111]
	v_pk_mul_f32 v[100:101], v[98:99], v[108:109]
	v_pk_mul_f32 v[98:99], v[124:125], v[106:107]
	v_pk_mul_f32 v[96:97], v[126:127], v[104:105]
	v_pk_mul_f32 v[106:107], v[146:147], v[118:119]
	v_pk_mul_f32 v[110:111], v[156:157], v[116:117]
	v_pk_mul_f32 v[104:105], v[158:159], v[122:123]
	v_pk_mul_f32 v[108:109], v[112:113], v[120:121]
	s_cbranch_vccnz .LBB0_624
	v_lshlrev_b32_e32 v112, 6, v114
	s_mov_b32 s0, 0x1f7c0
	v_and_or_b32 v112, v112, s0, v154
	v_lshlrev_b32_e32 v112, 2, v112
	s_waitcnt vmcnt(6)
	v_mov_b64_e32 v[116:117], v[212:213]
	v_mov_b64_e32 v[118:119], v[214:215]
	v_mov_b64_e32 v[120:121], v[216:217]
	v_mov_b64_e32 v[122:123], v[218:219]
	v_mov_b64_e32 v[124:125], v[220:221]
	v_mov_b64_e32 v[126:127], v[222:223]
	v_mov_b64_e32 v[156:157], v[224:225]
	v_mov_b64_e32 v[158:159], v[226:227]
	v_add_u32_e32 v242, 0x3000, v245
	global_load_dwordx4 v[212:215], v242, s[46:47] offset:16
	global_load_dwordx4 v[216:219], v242, s[46:47]
	global_load_dwordx4 v[220:223], v242, s[26:27] offset:16
	global_load_dwordx4 v[224:227], v242, s[26:27]
	s_mov_b64 s[60:61], 0x80
	v_pk_mul_f32 v[112:113], v[106:107], v[158:159]
	v_pk_mul_f32 v[146:147], v[110:111], v[156:157]
	v_pk_fma_f32 v[162:163], v[102:103], v[122:123], v[112:113] neg_lo:[0,0,1] neg_hi:[0,0,1]
	v_pk_fma_f32 v[160:161], v[100:101], v[120:121], v[146:147] neg_lo:[0,0,1] neg_hi:[0,0,1]
	v_pk_mul_f32 v[102:103], v[102:103], v[158:159]
	v_pk_mul_f32 v[100:101], v[100:101], v[156:157]
	v_pk_fma_f32 v[106:107], v[106:107], v[122:123], v[102:103]
	v_pk_fma_f32 v[110:111], v[110:111], v[120:121], v[100:101]
	v_pk_mul_f32 v[100:101], v[104:105], v[126:127]
	v_pk_mul_f32 v[102:103], v[108:109], v[124:125]
	v_pk_fma_f32 v[122:123], v[98:99], v[118:119], v[100:101] neg_lo:[0,0,1] neg_hi:[0,0,1]
	v_pk_fma_f32 v[120:121], v[96:97], v[116:117], v[102:103] neg_lo:[0,0,1] neg_hi:[0,0,1]
	v_pk_mul_f32 v[98:99], v[98:99], v[126:127]
	v_pk_mul_f32 v[96:97], v[96:97], v[124:125]
	v_pk_fma_f32 v[104:105], v[104:105], v[118:119], v[98:99]
	v_pk_fma_f32 v[108:109], v[108:109], v[116:117], v[96:97]
	v_mov_b64_e32 v[100:101], v[160:161]
	v_mov_b64_e32 v[96:97], v[120:121]
	v_mov_b64_e32 v[112:113], v[128:129]
	v_mov_b64_e32 v[102:103], v[162:163]
	v_mov_b64_e32 v[98:99], v[122:123]
	s_branch .LBB0_625

;     __device__ __forceinline__ void operator()(Acc& acc, const Unit& u, int wr, int wc, int fr, int fq, LAS unsigned char* lds, int tid) const {
;     ...
;             for (int m = 0; m < 4; ++m) {
;                 const unsigned row = row0 + ai * 128 + wr * 64 + m * 16 + fr;
;                 const float rs = *(const float*)((const char*)sx + (row << 2));
;                 f32x4 x[2][2];
; #pragma unroll
;                 for (int bj = 0; bj < 2; ++bj)
; #pragma unroll
;                     for (int n = 0; n < 2; ++n) { const pg8::i32x4 iv = __builtin_bit_cast(pg8::i32x4, acc[ai][bj][m][n]); x[bj][n] = __builtin_convertvector(iv, f32x4) * (swv[bj][n] * rs); }
;                 if (rope) {
;                     const unsigned t = row & (SEQ - 1), d0 = 32 * (wc & 1) + 8 * fq;
;                     f32x4 v[2][2];
; #pragma unroll
;                     for (int n = 0; n < 2; ++n) { const f32x4 c = ldf4(ropec, t * 64 + d0 + 4u * n), s = ldf4(ropes, t * 64 + d0 + 4u * n);
;                         v[0][n] = x[0][n] * c - x[1][n] * s; v[1][n] = x[1][n] * c + x[0][n] * s; }
;                     h16* o = Hq + (size_t)row * 3072 + (256 * pn + 128 * (wc >> 1) + d0);
;                     store_h8(o, v[0][0], v[0][1]); store_h8(o + 64, v[1][0], v[1][1]);
;                 } else {
;                     h16* o = Hq + (size_t)row * 3072 + colt;
;                     store_h8(o, x[0][0], x[0][1]); store_h8(o + 128, x[1][0], x[1][1]);
.LBB0_625:
	v_mov_b64_e32 v[116:117], s[76:77]
	v_mad_u64_u32 v[114:115], s[0:1], v114, s35, v[116:117]
	v_lshl_add_u64 v[112:113], v[112:113], 1, v[114:115]
	v_cvt_pk_f16_f32 v100, v100, v101
	v_cvt_pk_f16_f32 v101, v102, v103
	v_cvt_pk_f16_f32 v102, v96, v97
	v_cvt_pk_f16_f32 v103, v98, v99
	global_store_dwordx4 v[112:113], v[100:103], off
	v_cvt_pk_f16_f32 v96, v110, v111
	v_cvt_pk_f16_f32 v97, v106, v107
	v_lshl_add_u64 v[100:101], v[112:113], 0, s[60:61]
	v_cvt_pk_f16_f32 v98, v108, v109
	v_cvt_pk_f16_f32 v99, v104, v105
	global_store_dwordx4 v[100:101], v[96:99], off
	v_cvt_f32_i32_e32 v93, v93
	v_cvt_f32_i32_e32 v92, v92
	v_or_b32_e32 v98, 32, v155
	v_lshlrev_b32_e32 v96, 2, v98
	v_cvt_f32_i32_e32 v95, v95
	v_cvt_f32_i32_e32 v94, v94
	v_cvt_f32_i32_e32 v89, v89
	v_cvt_f32_i32_e32 v88, v88
	v_cvt_f32_i32_e32 v91, v91
	v_cvt_f32_i32_e32 v90, v90
	v_cvt_f32_i32_e32 v101, v85
	v_cvt_f32_i32_e32 v100, v84
	v_cvt_f32_i32_e32 v103, v87
	v_cvt_f32_i32_e32 v102, v86
	v_cvt_f32_i32_e32 v105, v81
	v_cvt_f32_i32_e32 v104, v80
	v_cvt_f32_i32_e32 v107, v83
	v_cvt_f32_i32_e32 v106, v82
	s_and_b64 vcc, exec, s[38:39]
	s_mov_b64 s[44:45], 0x100
	v_mov_b32_e32 v96, v178
	v_pk_mul_f32 v[80:81], v[132:133], v[96:97] op_sel_hi:[1,0]
	v_pk_mul_f32 v[82:83], v[136:137], v[96:97] op_sel_hi:[1,0]
	v_pk_mul_f32 v[108:109], v[130:131], v[96:97] op_sel_hi:[1,0]
	v_pk_mul_f32 v[110:111], v[134:135], v[96:97] op_sel_hi:[1,0]
	v_pk_mul_f32 v[112:113], v[140:141], v[96:97] op_sel_hi:[1,0]
	v_pk_mul_f32 v[114:115], v[144:145], v[96:97] op_sel_hi:[1,0]
	v_pk_mul_f32 v[116:117], v[138:139], v[96:97] op_sel_hi:[1,0]
	v_pk_mul_f32 v[96:97], v[142:143], v[96:97] op_sel_hi:[1,0]
	v_pk_mul_f32 v[86:87], v[80:81], v[94:95]
	v_pk_mul_f32 v[84:85], v[82:83], v[92:93]
	v_pk_mul_f32 v[82:83], v[108:109], v[90:91]
	v_pk_mul_f32 v[80:81], v[110:111], v[88:89]
	v_pk_mul_f32 v[90:91], v[112:113], v[102:103]
	v_pk_mul_f32 v[94:95], v[114:115], v[100:101]
	v_pk_mul_f32 v[88:89], v[116:117], v[106:107]
	v_pk_mul_f32 v[92:93], v[96:97], v[104:105]
	s_cbranch_vccnz .LBB0_627
	v_lshlrev_b32_e32 v96, 6, v98
	s_mov_b32 s0, 0x1fbc0
	v_and_or_b32 v96, v96, s0, v154
	v_lshlrev_b32_e32 v96, 2, v96
	s_waitcnt vmcnt(8)
	v_mov_b64_e32 v[100:101], v[184:185]
	v_mov_b64_e32 v[102:103], v[186:187]
	v_mov_b64_e32 v[104:105], v[188:189]
	v_mov_b64_e32 v[106:107], v[190:191]
	v_mov_b64_e32 v[108:109], v[192:193]
	v_mov_b64_e32 v[110:111], v[194:195]
	v_mov_b64_e32 v[112:113], v[196:197]
	v_mov_b64_e32 v[114:115], v[198:199]
	v_add_u32_e32 v242, 0x8000, v245
	global_load_dwordx4 v[184:187], v242, s[46:47] offset:16
	global_load_dwordx4 v[188:191], v242, s[46:47]
	global_load_dwordx4 v[192:195], v242, s[26:27] offset:16
	global_load_dwordx4 v[196:199], v242, s[26:27]
	s_mov_b64 s[56:57], 0x80
	v_pk_mul_f32 v[96:97], v[90:91], v[114:115]
	v_pk_mul_f32 v[116:117], v[94:95], v[112:113]
	v_pk_fma_f32 v[118:119], v[86:87], v[106:107], v[96:97] neg_lo:[0,0,1] neg_hi:[0,0,1]
	v_pk_fma_f32 v[116:117], v[84:85], v[104:105], v[116:117] neg_lo:[0,0,1] neg_hi:[0,0,1]
	v_pk_mul_f32 v[86:87], v[86:87], v[114:115]
	v_pk_mul_f32 v[84:85], v[84:85], v[112:113]
	v_pk_fma_f32 v[90:91], v[90:91], v[106:107], v[86:87]
	v_pk_fma_f32 v[94:95], v[94:95], v[104:105], v[84:85]
	v_pk_mul_f32 v[84:85], v[88:89], v[110:111]
	v_pk_mul_f32 v[86:87], v[92:93], v[108:109]
	v_pk_fma_f32 v[106:107], v[82:83], v[102:103], v[84:85] neg_lo:[0,0,1] neg_hi:[0,0,1]
	v_pk_fma_f32 v[104:105], v[80:81], v[100:101], v[86:87] neg_lo:[0,0,1] neg_hi:[0,0,1]
	v_pk_mul_f32 v[82:83], v[82:83], v[110:111]
	v_pk_mul_f32 v[80:81], v[80:81], v[108:109]
	v_pk_fma_f32 v[88:89], v[88:89], v[102:103], v[82:83]
	v_pk_fma_f32 v[92:93], v[92:93], v[100:101], v[80:81]
	v_mov_b64_e32 v[84:85], v[116:117]
	v_mov_b64_e32 v[80:81], v[104:105]
	v_mov_b64_e32 v[96:97], v[128:129]
	v_mov_b64_e32 v[86:87], v[118:119]
	v_mov_b64_e32 v[82:83], v[106:107]
	s_branch .LBB0_628

;     __device__ __forceinline__ void operator()(Acc& acc, const Unit& u, int wr, int wc, int fr, int fq, LAS unsigned char* lds, int tid) const {
;     ...
;             for (int m = 0; m < 4; ++m) {
;                 const unsigned row = row0 + ai * 128 + wr * 64 + m * 16 + fr;
;                 const float rs = *(const float*)((const char*)sx + (row << 2));
;                 f32x4 x[2][2];
; #pragma unroll
;                 for (int bj = 0; bj < 2; ++bj)
; #pragma unroll
;                     for (int n = 0; n < 2; ++n) { const pg8::i32x4 iv = __builtin_bit_cast(pg8::i32x4, acc[ai][bj][m][n]); x[bj][n] = __builtin_convertvector(iv, f32x4) * (swv[bj][n] * rs); }
;                 if (rope) {
;                     const unsigned t = row & (SEQ - 1), d0 = 32 * (wc & 1) + 8 * fq;
;                     f32x4 v[2][2];
; #pragma unroll
;                     for (int n = 0; n < 2; ++n) { const f32x4 c = ldf4(ropec, t * 64 + d0 + 4u * n), s = ldf4(ropes, t * 64 + d0 + 4u * n);
;                         v[0][n] = x[0][n] * c - x[1][n] * s; v[1][n] = x[1][n] * c + x[0][n] * s; }
;                     h16* o = Hq + (size_t)row * 3072 + (256 * pn + 128 * (wc >> 1) + d0);
;                     store_h8(o, v[0][0], v[0][1]); store_h8(o + 64, v[1][0], v[1][1]);
;                 } else {
;                     h16* o = Hq + (size_t)row * 3072 + colt;
;                     store_h8(o, x[0][0], x[0][1]); store_h8(o + 128, x[1][0], x[1][1]);
.LBB0_628:
	v_mov_b64_e32 v[100:101], s[76:77]
	v_mad_u64_u32 v[98:99], s[0:1], v98, s35, v[100:101]
	v_lshl_add_u64 v[96:97], v[96:97], 1, v[98:99]
	v_cvt_pk_f16_f32 v84, v84, v85
	v_cvt_pk_f16_f32 v85, v86, v87
	v_cvt_pk_f16_f32 v86, v80, v81
	v_cvt_pk_f16_f32 v87, v82, v83
	global_store_dwordx4 v[96:97], v[84:87], off
	v_cvt_pk_f16_f32 v80, v94, v95
	v_cvt_pk_f16_f32 v81, v90, v91
	v_lshl_add_u64 v[84:85], v[96:97], 0, s[56:57]
	v_cvt_pk_f16_f32 v82, v92, v93
	v_cvt_pk_f16_f32 v83, v88, v89
	global_store_dwordx4 v[84:85], v[80:83], off
	v_cvt_f32_i32_e32 v77, v77
	v_cvt_f32_i32_e32 v76, v76
	v_or_b32_e32 v82, 48, v155
	v_lshlrev_b32_e32 v80, 2, v82
	v_cvt_f32_i32_e32 v79, v79
	v_cvt_f32_i32_e32 v78, v78
	v_cvt_f32_i32_e32 v73, v73
	v_cvt_f32_i32_e32 v72, v72
	v_cvt_f32_i32_e32 v75, v75
	v_cvt_f32_i32_e32 v74, v74
	v_cvt_f32_i32_e32 v85, v69
	v_cvt_f32_i32_e32 v84, v68
	v_cvt_f32_i32_e32 v87, v71
	v_cvt_f32_i32_e32 v86, v70
	v_cvt_f32_i32_e32 v89, v65
	v_cvt_f32_i32_e32 v88, v64
	v_cvt_f32_i32_e32 v91, v67
	v_cvt_f32_i32_e32 v90, v66
	s_and_b64 vcc, exec, s[38:39]
	v_mov_b32_e32 v80, v179
	v_pk_mul_f32 v[64:65], v[132:133], v[80:81] op_sel_hi:[1,0]
	v_pk_mul_f32 v[66:67], v[136:137], v[80:81] op_sel_hi:[1,0]
	v_pk_mul_f32 v[92:93], v[130:131], v[80:81] op_sel_hi:[1,0]
	v_pk_mul_f32 v[94:95], v[134:135], v[80:81] op_sel_hi:[1,0]
	v_pk_mul_f32 v[96:97], v[140:141], v[80:81] op_sel_hi:[1,0]
	v_pk_mul_f32 v[98:99], v[144:145], v[80:81] op_sel_hi:[1,0]
	v_pk_mul_f32 v[100:101], v[138:139], v[80:81] op_sel_hi:[1,0]
	v_pk_mul_f32 v[80:81], v[142:143], v[80:81] op_sel_hi:[1,0]
	v_pk_mul_f32 v[70:71], v[64:65], v[78:79]
	v_pk_mul_f32 v[68:69], v[66:67], v[76:77]
	v_pk_mul_f32 v[66:67], v[92:93], v[74:75]
	v_pk_mul_f32 v[64:65], v[94:95], v[72:73]
	v_pk_mul_f32 v[74:75], v[96:97], v[86:87]
	v_pk_mul_f32 v[78:79], v[98:99], v[84:85]
	v_pk_mul_f32 v[72:73], v[100:101], v[90:91]
	v_pk_mul_f32 v[76:77], v[80:81], v[88:89]
	s_cbranch_vccnz .LBB0_630
	v_lshlrev_b32_e32 v80, 6, v82
	s_mov_b32 s0, 0x1ffc0
	v_and_or_b32 v80, v80, s0, v154
	v_lshlrev_b32_e32 v80, 2, v80
	s_waitcnt vmcnt(8)
	v_mov_b64_e32 v[84:85], v[212:213]
	v_mov_b64_e32 v[86:87], v[214:215]
	v_mov_b64_e32 v[88:89], v[216:217]
	v_mov_b64_e32 v[90:91], v[218:219]
	v_mov_b64_e32 v[92:93], v[220:221]
	v_mov_b64_e32 v[94:95], v[222:223]
	v_mov_b64_e32 v[96:97], v[224:225]
	v_mov_b64_e32 v[98:99], v[226:227]
	v_add_u32_e32 v242, 0x9000, v245
	global_load_dwordx4 v[212:215], v242, s[46:47] offset:16
	global_load_dwordx4 v[216:219], v242, s[46:47]
	global_load_dwordx4 v[220:223], v242, s[26:27] offset:16
	global_load_dwordx4 v[224:227], v242, s[26:27]
	s_mov_b64 s[44:45], 0x80
	v_pk_mul_f32 v[80:81], v[74:75], v[98:99]
	v_pk_mul_f32 v[100:101], v[78:79], v[96:97]
	v_pk_fma_f32 v[102:103], v[70:71], v[90:91], v[80:81] neg_lo:[0,0,1] neg_hi:[0,0,1]
	v_pk_fma_f32 v[100:101], v[68:69], v[88:89], v[100:101] neg_lo:[0,0,1] neg_hi:[0,0,1]
	v_pk_mul_f32 v[70:71], v[70:71], v[98:99]
	v_pk_mul_f32 v[68:69], v[68:69], v[96:97]
	v_pk_fma_f32 v[74:75], v[74:75], v[90:91], v[70:71]
	v_pk_fma_f32 v[78:79], v[78:79], v[88:89], v[68:69]
	v_pk_mul_f32 v[68:69], v[72:73], v[94:95]
	v_pk_mul_f32 v[70:71], v[76:77], v[92:93]
	v_pk_fma_f32 v[90:91], v[66:67], v[86:87], v[68:69] neg_lo:[0,0,1] neg_hi:[0,0,1]
	v_pk_fma_f32 v[88:89], v[64:65], v[84:85], v[70:71] neg_lo:[0,0,1] neg_hi:[0,0,1]
	v_pk_mul_f32 v[66:67], v[66:67], v[94:95]
	v_pk_mul_f32 v[64:65], v[64:65], v[92:93]
	v_pk_fma_f32 v[72:73], v[72:73], v[86:87], v[66:67]
	v_pk_fma_f32 v[76:77], v[76:77], v[84:85], v[64:65]
	v_mov_b64_e32 v[68:69], v[100:101]
	v_mov_b64_e32 v[64:65], v[88:89]
	v_mov_b64_e32 v[80:81], v[128:129]
	v_mov_b64_e32 v[70:71], v[102:103]
	v_mov_b64_e32 v[66:67], v[90:91]
	s_branch .LBB0_631

;     __device__ __forceinline__ void operator()(Acc& acc, const Unit& u, int wr, int wc, int fr, int fq, LAS unsigned char* lds, int tid) const {
;     ...
;             for (int m = 0; m < 4; ++m) {
;                 const unsigned row = row0 + ai * 128 + wr * 64 + m * 16 + fr;
;                 const float rs = *(const float*)((const char*)sx + (row << 2));
;                 f32x4 x[2][2];
; #pragma unroll
;                 for (int bj = 0; bj < 2; ++bj)
; #pragma unroll
;                     for (int n = 0; n < 2; ++n) { const pg8::i32x4 iv = __builtin_bit_cast(pg8::i32x4, acc[ai][bj][m][n]); x[bj][n] = __builtin_convertvector(iv, f32x4) * (swv[bj][n] * rs); }
;                 if (rope) {
;                     const unsigned t = row & (SEQ - 1), d0 = 32 * (wc & 1) + 8 * fq;
;                     f32x4 v[2][2];
; #pragma unroll
;                     for (int n = 0; n < 2; ++n) { const f32x4 c = ldf4(ropec, t * 64 + d0 + 4u * n), s = ldf4(ropes, t * 64 + d0 + 4u * n);
;                         v[0][n] = x[0][n] * c - x[1][n] * s; v[1][n] = x[1][n] * c + x[0][n] * s; }
;                     h16* o = Hq + (size_t)row * 3072 + (256 * pn + 128 * (wc >> 1) + d0);
;                     store_h8(o, v[0][0], v[0][1]); store_h8(o + 64, v[1][0], v[1][1]);
;                 } else {
;                     h16* o = Hq + (size_t)row * 3072 + colt;
;                     store_h8(o, x[0][0], x[0][1]); store_h8(o + 128, x[1][0], x[1][1]);
.LBB0_631:
	v_mov_b64_e32 v[84:85], s[76:77]
	v_mad_u64_u32 v[82:83], s[0:1], v82, s35, v[84:85]
	v_lshl_add_u64 v[80:81], v[80:81], 1, v[82:83]
	v_cvt_pk_f16_f32 v68, v68, v69
	v_cvt_pk_f16_f32 v69, v70, v71
	v_cvt_pk_f16_f32 v70, v64, v65
	v_cvt_pk_f16_f32 v71, v66, v67
	global_store_dwordx4 v[80:81], v[68:71], off
	v_cvt_pk_f16_f32 v64, v78, v79
	v_cvt_pk_f16_f32 v65, v74, v75
	v_lshl_add_u64 v[68:69], v[80:81], 0, s[44:45]
	v_cvt_pk_f16_f32 v66, v76, v77
	v_cvt_pk_f16_f32 v67, v72, v73
	global_store_dwordx4 v[68:69], v[64:67], off
	v_cvt_f32_i32_e32 v61, v61
	v_cvt_f32_i32_e32 v60, v60
	v_add_u32_e32 v66, 0x80, v155
	v_lshlrev_b32_e32 v64, 2, v66
	v_cvt_f32_i32_e32 v63, v63
	v_cvt_f32_i32_e32 v62, v62
	v_cvt_f32_i32_e32 v57, v57
	v_cvt_f32_i32_e32 v56, v56
	v_cvt_f32_i32_e32 v59, v59
	v_cvt_f32_i32_e32 v58, v58
	v_cvt_f32_i32_e32 v69, v53
	v_cvt_f32_i32_e32 v68, v52
	v_cvt_f32_i32_e32 v71, v55
	v_cvt_f32_i32_e32 v70, v54
	v_cvt_f32_i32_e32 v73, v49
	v_cvt_f32_i32_e32 v72, v48
	v_cvt_f32_i32_e32 v75, v51
	v_cvt_f32_i32_e32 v74, v50
	s_and_b64 vcc, exec, s[38:39]
	s_mov_b64 s[44:45], 0x100
	v_mov_b32_e32 v64, v180
	v_pk_mul_f32 v[48:49], v[132:133], v[64:65] op_sel_hi:[1,0]
	v_pk_mul_f32 v[50:51], v[136:137], v[64:65] op_sel_hi:[1,0]
	v_pk_mul_f32 v[76:77], v[130:131], v[64:65] op_sel_hi:[1,0]
	v_pk_mul_f32 v[78:79], v[134:135], v[64:65] op_sel_hi:[1,0]
	v_pk_mul_f32 v[80:81], v[140:141], v[64:65] op_sel_hi:[1,0]
	v_pk_mul_f32 v[82:83], v[144:145], v[64:65] op_sel_hi:[1,0]
	v_pk_mul_f32 v[84:85], v[138:139], v[64:65] op_sel_hi:[1,0]
	v_pk_mul_f32 v[64:65], v[142:143], v[64:65] op_sel_hi:[1,0]
	v_pk_mul_f32 v[54:55], v[48:49], v[62:63]
	v_pk_mul_f32 v[52:53], v[50:51], v[60:61]
	v_pk_mul_f32 v[50:51], v[76:77], v[58:59]
	v_pk_mul_f32 v[48:49], v[78:79], v[56:57]
	v_pk_mul_f32 v[58:59], v[80:81], v[70:71]
	v_pk_mul_f32 v[62:63], v[82:83], v[68:69]
	v_pk_mul_f32 v[56:57], v[84:85], v[74:75]
	v_pk_mul_f32 v[60:61], v[64:65], v[72:73]
	s_cbranch_vccnz .LBB0_633
	v_lshlrev_b32_e32 v64, 6, v66
	s_mov_b32 s0, 0x1f3c0
	v_and_or_b32 v64, v64, s0, v154
	v_lshlrev_b32_e32 v64, 2, v64
	s_waitcnt vmcnt(8)
	v_mov_b64_e32 v[68:69], v[184:185]
	v_mov_b64_e32 v[70:71], v[186:187]
	v_mov_b64_e32 v[72:73], v[188:189]
	v_mov_b64_e32 v[74:75], v[190:191]
	v_mov_b64_e32 v[76:77], v[192:193]
	v_mov_b64_e32 v[78:79], v[194:195]
	v_mov_b64_e32 v[80:81], v[196:197]
	v_mov_b64_e32 v[82:83], v[198:199]
	v_add_u32_e32 v242, 0xa000, v245
	global_load_dwordx4 v[184:187], v242, s[46:47] offset:16
	global_load_dwordx4 v[188:191], v242, s[46:47]
	global_load_dwordx4 v[192:195], v242, s[26:27] offset:16
	global_load_dwordx4 v[196:199], v242, s[26:27]
	s_mov_b64 s[56:57], 0x80
	v_pk_mul_f32 v[64:65], v[58:59], v[82:83]
	v_pk_mul_f32 v[84:85], v[62:63], v[80:81]
	v_pk_fma_f32 v[86:87], v[54:55], v[74:75], v[64:65] neg_lo:[0,0,1] neg_hi:[0,0,1]
	v_pk_fma_f32 v[84:85], v[52:53], v[72:73], v[84:85] neg_lo:[0,0,1] neg_hi:[0,0,1]
	v_pk_mul_f32 v[54:55], v[54:55], v[82:83]
	v_pk_mul_f32 v[52:53], v[52:53], v[80:81]
	v_pk_fma_f32 v[58:59], v[58:59], v[74:75], v[54:55]
	v_pk_fma_f32 v[62:63], v[62:63], v[72:73], v[52:53]
	v_pk_mul_f32 v[52:53], v[56:57], v[78:79]
	v_pk_mul_f32 v[54:55], v[60:61], v[76:77]
	v_pk_fma_f32 v[74:75], v[50:51], v[70:71], v[52:53] neg_lo:[0,0,1] neg_hi:[0,0,1]
	v_pk_fma_f32 v[72:73], v[48:49], v[68:69], v[54:55] neg_lo:[0,0,1] neg_hi:[0,0,1]
	v_pk_mul_f32 v[50:51], v[50:51], v[78:79]
	v_pk_mul_f32 v[48:49], v[48:49], v[76:77]
	v_pk_fma_f32 v[56:57], v[56:57], v[70:71], v[50:51]
	v_pk_fma_f32 v[60:61], v[60:61], v[68:69], v[48:49]
	v_mov_b64_e32 v[52:53], v[84:85]
	v_mov_b64_e32 v[48:49], v[72:73]
	v_mov_b64_e32 v[64:65], v[128:129]
	v_mov_b64_e32 v[54:55], v[86:87]
	v_mov_b64_e32 v[50:51], v[74:75]
	s_branch .LBB0_634

;     __device__ __forceinline__ void operator()(Acc& acc, const Unit& u, int wr, int wc, int fr, int fq, LAS unsigned char* lds, int tid) const {
;     ...
;             for (int m = 0; m < 4; ++m) {
;                 const unsigned row = row0 + ai * 128 + wr * 64 + m * 16 + fr;
;                 const float rs = *(const float*)((const char*)sx + (row << 2));
;                 f32x4 x[2][2];
; #pragma unroll
;                 for (int bj = 0; bj < 2; ++bj)
; #pragma unroll
;                     for (int n = 0; n < 2; ++n) { const pg8::i32x4 iv = __builtin_bit_cast(pg8::i32x4, acc[ai][bj][m][n]); x[bj][n] = __builtin_convertvector(iv, f32x4) * (swv[bj][n] * rs); }
;                 if (rope) {
;                     const unsigned t = row & (SEQ - 1), d0 = 32 * (wc & 1) + 8 * fq;
;                     f32x4 v[2][2];
; #pragma unroll
;                     for (int n = 0; n < 2; ++n) { const f32x4 c = ldf4(ropec, t * 64 + d0 + 4u * n), s = ldf4(ropes, t * 64 + d0 + 4u * n);
;                         v[0][n] = x[0][n] * c - x[1][n] * s; v[1][n] = x[1][n] * c + x[0][n] * s; }
;                     h16* o = Hq + (size_t)row * 3072 + (256 * pn + 128 * (wc >> 1) + d0);
;                     store_h8(o, v[0][0], v[0][1]); store_h8(o + 64, v[1][0], v[1][1]);
;                 } else {
;                     h16* o = Hq + (size_t)row * 3072 + colt;
;                     store_h8(o, x[0][0], x[0][1]); store_h8(o + 128, x[1][0], x[1][1]);
.LBB0_634:
	v_mov_b64_e32 v[68:69], s[76:77]
	v_mad_u64_u32 v[66:67], s[0:1], v66, s35, v[68:69]
	v_lshl_add_u64 v[64:65], v[64:65], 1, v[66:67]
	v_cvt_pk_f16_f32 v52, v52, v53
	v_cvt_pk_f16_f32 v53, v54, v55
	v_cvt_pk_f16_f32 v54, v48, v49
	v_cvt_pk_f16_f32 v55, v50, v51
	global_store_dwordx4 v[64:65], v[52:55], off
	v_cvt_pk_f16_f32 v48, v62, v63
	v_cvt_pk_f16_f32 v49, v58, v59
	v_lshl_add_u64 v[52:53], v[64:65], 0, s[56:57]
	v_cvt_pk_f16_f32 v50, v60, v61
	v_cvt_pk_f16_f32 v51, v56, v57
	global_store_dwordx4 v[52:53], v[48:51], off
	v_cvt_f32_i32_e32 v45, v45
	v_cvt_f32_i32_e32 v44, v44
	v_add_u32_e32 v50, 0x90, v155
	v_lshlrev_b32_e32 v48, 2, v50
	v_cvt_f32_i32_e32 v47, v47
	v_cvt_f32_i32_e32 v46, v46
	v_cvt_f32_i32_e32 v41, v41
	v_cvt_f32_i32_e32 v40, v40
	v_cvt_f32_i32_e32 v43, v43
	v_cvt_f32_i32_e32 v42, v42
	v_cvt_f32_i32_e32 v53, v37
	v_cvt_f32_i32_e32 v52, v36
	v_cvt_f32_i32_e32 v55, v39
	v_cvt_f32_i32_e32 v54, v38
	v_cvt_f32_i32_e32 v57, v33
	v_cvt_f32_i32_e32 v56, v32
	v_cvt_f32_i32_e32 v59, v35
	v_cvt_f32_i32_e32 v58, v34
	s_and_b64 vcc, exec, s[38:39]
	v_mov_b32_e32 v48, v181
	v_pk_mul_f32 v[32:33], v[132:133], v[48:49] op_sel_hi:[1,0]
	v_pk_mul_f32 v[34:35], v[136:137], v[48:49] op_sel_hi:[1,0]
	v_pk_mul_f32 v[60:61], v[130:131], v[48:49] op_sel_hi:[1,0]
	v_pk_mul_f32 v[62:63], v[134:135], v[48:49] op_sel_hi:[1,0]
	v_pk_mul_f32 v[64:65], v[140:141], v[48:49] op_sel_hi:[1,0]
	v_pk_mul_f32 v[66:67], v[144:145], v[48:49] op_sel_hi:[1,0]
	v_pk_mul_f32 v[68:69], v[138:139], v[48:49] op_sel_hi:[1,0]
	v_pk_mul_f32 v[48:49], v[142:143], v[48:49] op_sel_hi:[1,0]
	v_pk_mul_f32 v[38:39], v[32:33], v[46:47]
	v_pk_mul_f32 v[36:37], v[34:35], v[44:45]
	v_pk_mul_f32 v[34:35], v[60:61], v[42:43]
	v_pk_mul_f32 v[32:33], v[62:63], v[40:41]
	v_pk_mul_f32 v[42:43], v[64:65], v[54:55]
	v_pk_mul_f32 v[46:47], v[66:67], v[52:53]
	v_pk_mul_f32 v[40:41], v[68:69], v[58:59]
	v_pk_mul_f32 v[44:45], v[48:49], v[56:57]
	s_cbranch_vccnz .LBB0_636
	v_lshlrev_b32_e32 v48, 6, v50
	s_mov_b32 s0, 0x1f7c0
	v_and_or_b32 v48, v48, s0, v154
	v_lshlrev_b32_e32 v48, 2, v48
	s_waitcnt vmcnt(8)
	v_mov_b64_e32 v[52:53], v[212:213]
	v_mov_b64_e32 v[54:55], v[214:215]
	v_mov_b64_e32 v[56:57], v[216:217]
	v_mov_b64_e32 v[58:59], v[218:219]
	v_mov_b64_e32 v[60:61], v[220:221]
	v_mov_b64_e32 v[62:63], v[222:223]
	v_mov_b64_e32 v[64:65], v[224:225]
	v_mov_b64_e32 v[66:67], v[226:227]
	v_add_u32_e32 v242, 0xb000, v245
	global_load_dwordx4 v[212:215], v242, s[46:47] offset:16
	global_load_dwordx4 v[216:219], v242, s[46:47]
	global_load_dwordx4 v[220:223], v242, s[26:27] offset:16
	global_load_dwordx4 v[224:227], v242, s[26:27]
	s_mov_b64 s[44:45], 0x80
	v_pk_mul_f32 v[48:49], v[42:43], v[66:67]
	v_pk_mul_f32 v[68:69], v[46:47], v[64:65]
	v_pk_fma_f32 v[70:71], v[38:39], v[58:59], v[48:49] neg_lo:[0,0,1] neg_hi:[0,0,1]
	v_pk_fma_f32 v[68:69], v[36:37], v[56:57], v[68:69] neg_lo:[0,0,1] neg_hi:[0,0,1]
	v_pk_mul_f32 v[38:39], v[38:39], v[66:67]
	v_pk_mul_f32 v[36:37], v[36:37], v[64:65]
	v_pk_fma_f32 v[42:43], v[42:43], v[58:59], v[38:39]
	v_pk_fma_f32 v[46:47], v[46:47], v[56:57], v[36:37]
	v_pk_mul_f32 v[36:37], v[40:41], v[62:63]
	v_pk_mul_f32 v[38:39], v[44:45], v[60:61]
	v_pk_fma_f32 v[58:59], v[34:35], v[54:55], v[36:37] neg_lo:[0,0,1] neg_hi:[0,0,1]
	v_pk_fma_f32 v[56:57], v[32:33], v[52:53], v[38:39] neg_lo:[0,0,1] neg_hi:[0,0,1]
	v_pk_mul_f32 v[34:35], v[34:35], v[62:63]
	v_pk_mul_f32 v[32:33], v[32:33], v[60:61]
	v_pk_fma_f32 v[40:41], v[40:41], v[54:55], v[34:35]
	v_pk_fma_f32 v[44:45], v[44:45], v[52:53], v[32:33]
	v_mov_b64_e32 v[36:37], v[68:69]
	v_mov_b64_e32 v[32:33], v[56:57]
	v_mov_b64_e32 v[48:49], v[128:129]
	v_mov_b64_e32 v[38:39], v[70:71]
	v_mov_b64_e32 v[34:35], v[58:59]
	s_branch .LBB0_637

;     __device__ __forceinline__ void operator()(Acc& acc, const Unit& u, int wr, int wc, int fr, int fq, LAS unsigned char* lds, int tid) const {
;     ...
;             for (int m = 0; m < 4; ++m) {
;                 const unsigned row = row0 + ai * 128 + wr * 64 + m * 16 + fr;
;                 const float rs = *(const float*)((const char*)sx + (row << 2));
;                 f32x4 x[2][2];
; #pragma unroll
;                 for (int bj = 0; bj < 2; ++bj)
; #pragma unroll
;                     for (int n = 0; n < 2; ++n) { const pg8::i32x4 iv = __builtin_bit_cast(pg8::i32x4, acc[ai][bj][m][n]); x[bj][n] = __builtin_convertvector(iv, f32x4) * (swv[bj][n] * rs); }
;                 if (rope) {
;                     const unsigned t = row & (SEQ - 1), d0 = 32 * (wc & 1) + 8 * fq;
;                     f32x4 v[2][2];
; #pragma unroll
;                     for (int n = 0; n < 2; ++n) { const f32x4 c = ldf4(ropec, t * 64 + d0 + 4u * n), s = ldf4(ropes, t * 64 + d0 + 4u * n);
;                         v[0][n] = x[0][n] * c - x[1][n] * s; v[1][n] = x[1][n] * c + x[0][n] * s; }
;                     h16* o = Hq + (size_t)row * 3072 + (256 * pn + 128 * (wc >> 1) + d0);
;                     store_h8(o, v[0][0], v[0][1]); store_h8(o + 64, v[1][0], v[1][1]);
;                 } else {
;                     h16* o = Hq + (size_t)row * 3072 + colt;
;                     store_h8(o, x[0][0], x[0][1]); store_h8(o + 128, x[1][0], x[1][1]);
.LBB0_637:
	v_mov_b64_e32 v[52:53], s[76:77]
	v_mad_u64_u32 v[50:51], s[0:1], v50, s35, v[52:53]
	v_lshl_add_u64 v[48:49], v[48:49], 1, v[50:51]
	v_cvt_pk_f16_f32 v36, v36, v37
	v_cvt_pk_f16_f32 v37, v38, v39
	v_cvt_pk_f16_f32 v38, v32, v33
	v_cvt_pk_f16_f32 v39, v34, v35
	global_store_dwordx4 v[48:49], v[36:39], off
	v_cvt_pk_f16_f32 v32, v46, v47
	v_cvt_pk_f16_f32 v33, v42, v43
	v_lshl_add_u64 v[36:37], v[48:49], 0, s[44:45]
	v_cvt_pk_f16_f32 v34, v44, v45
	v_cvt_pk_f16_f32 v35, v40, v41
	global_store_dwordx4 v[36:37], v[32:35], off
	v_cvt_f32_i32_e32 v29, v29
	v_cvt_f32_i32_e32 v28, v28
	v_add_u32_e32 v34, 0xa0, v155
	v_lshlrev_b32_e32 v32, 2, v34
	v_cvt_f32_i32_e32 v31, v31
	v_cvt_f32_i32_e32 v30, v30
	v_cvt_f32_i32_e32 v25, v25
	v_cvt_f32_i32_e32 v24, v24
	v_cvt_f32_i32_e32 v27, v27
	v_cvt_f32_i32_e32 v26, v26
	v_cvt_f32_i32_e32 v37, v21
	v_cvt_f32_i32_e32 v36, v20
	v_cvt_f32_i32_e32 v39, v23
	v_cvt_f32_i32_e32 v38, v22
	v_cvt_f32_i32_e32 v41, v17
	v_cvt_f32_i32_e32 v40, v16
	v_cvt_f32_i32_e32 v43, v19
	v_cvt_f32_i32_e32 v42, v18
	s_and_b64 vcc, exec, s[38:39]
	s_mov_b64 s[44:45], 0x100
	v_mov_b32_e32 v32, v182
	v_pk_mul_f32 v[16:17], v[132:133], v[32:33] op_sel_hi:[1,0]
	v_pk_mul_f32 v[18:19], v[136:137], v[32:33] op_sel_hi:[1,0]
	v_pk_mul_f32 v[44:45], v[130:131], v[32:33] op_sel_hi:[1,0]
	v_pk_mul_f32 v[46:47], v[134:135], v[32:33] op_sel_hi:[1,0]
	v_pk_mul_f32 v[48:49], v[140:141], v[32:33] op_sel_hi:[1,0]
	v_pk_mul_f32 v[50:51], v[144:145], v[32:33] op_sel_hi:[1,0]
	v_pk_mul_f32 v[52:53], v[138:139], v[32:33] op_sel_hi:[1,0]
	v_pk_mul_f32 v[32:33], v[142:143], v[32:33] op_sel_hi:[1,0]
	v_pk_mul_f32 v[22:23], v[16:17], v[30:31]
	v_pk_mul_f32 v[20:21], v[18:19], v[28:29]
	v_pk_mul_f32 v[18:19], v[44:45], v[26:27]
	v_pk_mul_f32 v[16:17], v[46:47], v[24:25]
	v_pk_mul_f32 v[26:27], v[48:49], v[38:39]
	v_pk_mul_f32 v[30:31], v[50:51], v[36:37]
	v_pk_mul_f32 v[24:25], v[52:53], v[42:43]
	v_pk_mul_f32 v[28:29], v[32:33], v[40:41]
	s_cbranch_vccnz .LBB0_639
	v_lshlrev_b32_e32 v32, 6, v34
	s_mov_b32 s0, 0x1fbc0
	v_and_or_b32 v32, v32, s0, v154
	v_lshlrev_b32_e32 v32, 2, v32
	s_waitcnt vmcnt(8)
	v_mov_b64_e32 v[36:37], v[184:185]
	v_mov_b64_e32 v[38:39], v[186:187]
	v_mov_b64_e32 v[40:41], v[188:189]
	v_mov_b64_e32 v[42:43], v[190:191]
	v_mov_b64_e32 v[44:45], v[192:193]
	v_mov_b64_e32 v[46:47], v[194:195]
	v_mov_b64_e32 v[48:49], v[196:197]
	v_mov_b64_e32 v[50:51], v[198:199]
	s_mov_b64 s[56:57], 0x80
	v_pk_mul_f32 v[32:33], v[26:27], v[50:51]
	v_pk_mul_f32 v[52:53], v[30:31], v[48:49]
	v_pk_fma_f32 v[54:55], v[22:23], v[42:43], v[32:33] neg_lo:[0,0,1] neg_hi:[0,0,1]
	v_pk_fma_f32 v[52:53], v[20:21], v[40:41], v[52:53] neg_lo:[0,0,1] neg_hi:[0,0,1]
	v_pk_mul_f32 v[22:23], v[22:23], v[50:51]
	v_pk_mul_f32 v[20:21], v[20:21], v[48:49]
	v_pk_fma_f32 v[26:27], v[26:27], v[42:43], v[22:23]
	v_pk_fma_f32 v[30:31], v[30:31], v[40:41], v[20:21]
	v_pk_mul_f32 v[20:21], v[24:25], v[46:47]
	v_pk_mul_f32 v[22:23], v[28:29], v[44:45]
	v_pk_fma_f32 v[42:43], v[18:19], v[38:39], v[20:21] neg_lo:[0,0,1] neg_hi:[0,0,1]
	v_pk_fma_f32 v[40:41], v[16:17], v[36:37], v[22:23] neg_lo:[0,0,1] neg_hi:[0,0,1]
	v_pk_mul_f32 v[18:19], v[18:19], v[46:47]
	v_pk_mul_f32 v[16:17], v[16:17], v[44:45]
	v_pk_fma_f32 v[24:25], v[24:25], v[38:39], v[18:19]
	v_pk_fma_f32 v[28:29], v[28:29], v[36:37], v[16:17]
	v_mov_b64_e32 v[20:21], v[52:53]
	v_mov_b64_e32 v[16:17], v[40:41]
	v_mov_b64_e32 v[32:33], v[128:129]
	v_mov_b64_e32 v[22:23], v[54:55]
	v_mov_b64_e32 v[18:19], v[42:43]
	s_branch .LBB0_640

;     __device__ __forceinline__ void operator()(Acc& acc, const Unit& u, int wr, int wc, int fr, int fq, LAS unsigned char* lds, int tid) const {
;     ...
;             for (int m = 0; m < 4; ++m) {
;                 const unsigned row = row0 + ai * 128 + wr * 64 + m * 16 + fr;
;                 const float rs = *(const float*)((const char*)sx + (row << 2));
;                 f32x4 x[2][2];
; #pragma unroll
;                 for (int bj = 0; bj < 2; ++bj)
; #pragma unroll
;                     for (int n = 0; n < 2; ++n) { const pg8::i32x4 iv = __builtin_bit_cast(pg8::i32x4, acc[ai][bj][m][n]); x[bj][n] = __builtin_convertvector(iv, f32x4) * (swv[bj][n] * rs); }
;                 if (rope) {
;                     const unsigned t = row & (SEQ - 1), d0 = 32 * (wc & 1) + 8 * fq;
;                     f32x4 v[2][2];
; #pragma unroll
;                     for (int n = 0; n < 2; ++n) { const f32x4 c = ldf4(ropec, t * 64 + d0 + 4u * n), s = ldf4(ropes, t * 64 + d0 + 4u * n);
;                         v[0][n] = x[0][n] * c - x[1][n] * s; v[1][n] = x[1][n] * c + x[0][n] * s; }
;                     h16* o = Hq + (size_t)row * 3072 + (256 * pn + 128 * (wc >> 1) + d0);
;                     store_h8(o, v[0][0], v[0][1]); store_h8(o + 64, v[1][0], v[1][1]);
;                 } else {
;                     h16* o = Hq + (size_t)row * 3072 + colt;
;                     store_h8(o, x[0][0], x[0][1]); store_h8(o + 128, x[1][0], x[1][1]);
.LBB0_640:
	v_mov_b64_e32 v[36:37], s[76:77]
	v_mad_u64_u32 v[34:35], s[0:1], v34, s35, v[36:37]
	v_lshl_add_u64 v[32:33], v[32:33], 1, v[34:35]
	v_cvt_pk_f16_f32 v20, v20, v21
	v_cvt_pk_f16_f32 v21, v22, v23
	v_cvt_pk_f16_f32 v22, v16, v17
	v_cvt_pk_f16_f32 v23, v18, v19
	global_store_dwordx4 v[32:33], v[20:23], off
	v_cvt_pk_f16_f32 v16, v30, v31
	v_cvt_pk_f16_f32 v17, v26, v27
	v_lshl_add_u64 v[20:21], v[32:33], 0, s[56:57]
	v_cvt_pk_f16_f32 v18, v28, v29
	v_cvt_pk_f16_f32 v19, v24, v25
	global_store_dwordx4 v[20:21], v[16:19], off
	v_cvt_f32_i32_e32 v13, v13
	v_cvt_f32_i32_e32 v12, v12
	v_add_u32_e32 v16, 0xb0, v155
	v_lshlrev_b32_e32 v17, 2, v16
	v_cvt_f32_i32_e32 v15, v15
	v_cvt_f32_i32_e32 v14, v14
	v_cvt_f32_i32_e32 v9, v9
	v_cvt_f32_i32_e32 v8, v8
	v_cvt_f32_i32_e32 v11, v11
	v_cvt_f32_i32_e32 v10, v10
	v_cvt_f32_i32_e32 v21, v5
	v_cvt_f32_i32_e32 v20, v4
	v_cvt_f32_i32_e32 v23, v7
	v_cvt_f32_i32_e32 v22, v6
	v_cvt_f32_i32_e32 v25, v1
	v_cvt_f32_i32_e32 v24, v0
	v_cvt_f32_i32_e32 v27, v3
	v_cvt_f32_i32_e32 v26, v2
	s_and_b64 vcc, exec, s[38:39]
	v_mov_b32_e32 v18, v183
	v_pk_mul_f32 v[0:1], v[132:133], v[18:19] op_sel_hi:[1,0]
	v_pk_mul_f32 v[2:3], v[136:137], v[18:19] op_sel_hi:[1,0]
	v_pk_mul_f32 v[28:29], v[130:131], v[18:19] op_sel_hi:[1,0]
	v_pk_mul_f32 v[30:31], v[134:135], v[18:19] op_sel_hi:[1,0]
	v_pk_mul_f32 v[32:33], v[140:141], v[18:19] op_sel_hi:[1,0]
	v_pk_mul_f32 v[34:35], v[144:145], v[18:19] op_sel_hi:[1,0]
	v_pk_mul_f32 v[36:37], v[138:139], v[18:19] op_sel_hi:[1,0]
	v_pk_mul_f32 v[18:19], v[142:143], v[18:19] op_sel_hi:[1,0]
	v_pk_mul_f32 v[6:7], v[0:1], v[14:15]
	v_pk_mul_f32 v[4:5], v[2:3], v[12:13]
	v_pk_mul_f32 v[2:3], v[28:29], v[10:11]
	v_pk_mul_f32 v[0:1], v[30:31], v[8:9]
	v_pk_mul_f32 v[10:11], v[32:33], v[22:23]
	v_pk_mul_f32 v[14:15], v[34:35], v[20:21]
	v_pk_mul_f32 v[8:9], v[36:37], v[26:27]
	v_pk_mul_f32 v[12:13], v[18:19], v[24:25]
	s_cbranch_vccnz .LBB0_642
	v_lshlrev_b32_e32 v17, 6, v16
	s_mov_b32 s0, 0x1ffc0
	v_and_or_b32 v17, v17, s0, v154
	v_lshlrev_b32_e32 v17, 2, v17
	s_waitcnt vmcnt(4)
	v_mov_b64_e32 v[18:19], v[212:213]
	v_mov_b64_e32 v[20:21], v[214:215]
	v_mov_b64_e32 v[22:23], v[216:217]
	v_mov_b64_e32 v[24:25], v[218:219]
	v_mov_b64_e32 v[26:27], v[220:221]
	v_mov_b64_e32 v[28:29], v[222:223]
	v_mov_b64_e32 v[30:31], v[224:225]
	v_mov_b64_e32 v[32:33], v[226:227]
	s_mov_b64 s[44:45], 0x80
	v_pk_mul_f32 v[34:35], v[10:11], v[32:33]
	v_pk_mul_f32 v[38:39], v[14:15], v[30:31]
	v_pk_fma_f32 v[36:37], v[6:7], v[24:25], v[34:35] neg_lo:[0,0,1] neg_hi:[0,0,1]
	v_pk_fma_f32 v[34:35], v[4:5], v[22:23], v[38:39] neg_lo:[0,0,1] neg_hi:[0,0,1]
	v_pk_mul_f32 v[6:7], v[6:7], v[32:33]
	v_pk_mul_f32 v[4:5], v[4:5], v[30:31]
	v_pk_fma_f32 v[10:11], v[10:11], v[24:25], v[6:7]
	v_pk_fma_f32 v[14:15], v[14:15], v[22:23], v[4:5]
	v_pk_mul_f32 v[4:5], v[8:9], v[28:29]
	v_pk_mul_f32 v[6:7], v[12:13], v[26:27]
	v_pk_fma_f32 v[24:25], v[2:3], v[20:21], v[4:5] neg_lo:[0,0,1] neg_hi:[0,0,1]
	v_pk_fma_f32 v[22:23], v[0:1], v[18:19], v[6:7] neg_lo:[0,0,1] neg_hi:[0,0,1]
	v_pk_mul_f32 v[2:3], v[2:3], v[28:29]
	v_pk_mul_f32 v[0:1], v[0:1], v[26:27]
	v_pk_fma_f32 v[8:9], v[8:9], v[20:21], v[2:3]
	v_pk_fma_f32 v[12:13], v[12:13], v[18:19], v[0:1]
	v_mov_b64_e32 v[4:5], v[34:35]
	v_mov_b64_e32 v[0:1], v[22:23]
	v_mov_b64_e32 v[6:7], v[36:37]
	v_mov_b64_e32 v[2:3], v[24:25]
	s_branch .LBB0_643
